# attention softmax: cross-half max exchange by v_permlane32_swap (VALU) instead of ds_bpermute + lgkmcnt(0) LDS round trips, 4 per iteration in both latent loops
# speedup vs baseline: 1.0007x; 1.0007x over previous
; #define LAS __attribute__((address_space(3)))
; template <int DK, bool IS_A>
; __device__ __forceinline__ void attn_unit(const Params& P, int l, LAS unsigned char* lds, int b, int grp, int qtok0, int nkeys) {
;     ...
;         for (int h = 0; h < 2; ++h) {
;             const LAS unsigned char* kb = lds + buf * A_BUF + kfo + h * 64 * AK_PITCH;
;             const LAS unsigned char* vb = lds + buf * A_BUF + vfo + h * 128;
;             f32x16 pa[2], pb[2];
; #pragma unroll
;             for (int jj = 0; jj < 2; ++jj)
; #pragma unroll
;                 for (int r = 0; r < 16; ++r) { pa[jj][r] = 0.f; pb[jj][r] = 0.f; }
;             __builtin_amdgcn_s_setprio(1);
; #pragma unroll
;             for (int i = 0; i < DK / 16; ++i)
; #pragma unroll
;                 for (int jj = 0; jj < 2; ++jj) {
;                     const bf16x8 kf = *(const LAS bf16x8*)(kb + jj * 32 * AK_PITCH + i * 32);
;                     pa[jj] = __builtin_amdgcn_mfma_f32_32x32x16_bf16(kf, qa[i], pa[jj], 0, 0, 0);
;                     pb[jj] = __builtin_amdgcn_mfma_f32_32x32x16_bf16(kf, qb[i], pb[jj], 0, 0, 0);
;                 }
;             __builtin_amdgcn_s_setprio(0);
.LBB0_420:
	s_mov_b32 s12, s100
	v_add_u32_e32 v64, s12, v177
	v_add_u32_e32 v187, v64, v179
	s_setprio 1
	ds_read_b128 v[64:67], v187
	ds_read_b128 v[188:191], v187 offset:32
	s_waitcnt lgkmcnt(1)
	v_mfma_f32_32x32x16_bf16 v[112:127], v[64:67], v[138:141], 0
	v_mfma_f32_32x32x16_bf16 v[96:111], v[64:67], v[146:149], 0
	ds_read_b128 v[64:67], v187 offset:4608
	s_waitcnt lgkmcnt(1)
	v_mfma_f32_32x32x16_bf16 v[112:127], v[188:191], v[142:145], v[112:127]
	v_mfma_f32_32x32x16_bf16 v[96:111], v[188:191], v[150:153], v[96:111]
	ds_read_b128 v[188:191], v187 offset:4640
	s_waitcnt lgkmcnt(1)
	v_mfma_f32_32x32x16_bf16 v[80:95], v[64:67], v[138:141], 0
	v_mfma_f32_32x32x16_bf16 v[64:79], v[64:67], v[146:149], 0
	s_waitcnt lgkmcnt(0)
	v_mfma_f32_32x32x16_bf16 v[80:95], v[188:191], v[142:145], v[80:95]
	v_mfma_f32_32x32x16_bf16 v[64:79], v[188:191], v[150:153], v[64:79]
	s_setprio 0
	s_nop 9
	v_max_f32_e32 v182, v80, v80
	v_max_f32_e32 v183, v112, v112
	v_max_f32_e32 v182, v183, v182
	v_max3_f32 v183, v81, v114, v82
	v_max3_f32 v182, v182, v113, v115
	v_max3_f32 v183, v183, v116, v84
	v_max3_f32 v182, v182, v83, v117
	v_max3_f32 v183, v183, v118, v86
	v_max3_f32 v182, v182, v85, v119
	v_max3_f32 v183, v183, v120, v88
	v_max3_f32 v182, v182, v87, v121
	v_max3_f32 v183, v183, v122, v90
	v_max3_f32 v182, v182, v89, v123
	v_max3_f32 v183, v183, v124, v92
	v_max3_f32 v182, v182, v91, v125
	v_max3_f32 v183, v183, v126, v94
	v_max3_f32 v182, v182, v93, v127
	v_max3_f32 v182, v182, v95, v183
	v_mov_b32_e32 v183, v182
	s_waitcnt lgkmcnt(0)
	s_nop 1
	v_permlane32_swap_b32_e32 v182, v183
	v_max3_f32 v188, v181, v182, v183
	v_cmp_gt_f32_e32 vcc, v188, v181
	s_cbranch_vccz .LBB0_422
	v_sub_f32_e32 v181, v181, v188
	v_exp_f32_e32 v182, v181
	s_nop 0
	v_pk_mul_f32 v[62:63], v[62:63], v[182:183] op_sel_hi:[1,0]
	v_pk_mul_f32 v[60:61], v[60:61], v[182:183] op_sel_hi:[1,0]
	v_pk_mul_f32 v[58:59], v[58:59], v[182:183] op_sel_hi:[1,0]
	v_pk_mul_f32 v[56:57], v[56:57], v[182:183] op_sel_hi:[1,0]
	v_pk_mul_f32 v[54:55], v[54:55], v[182:183] op_sel_hi:[1,0]
	v_pk_mul_f32 v[52:53], v[52:53], v[182:183] op_sel_hi:[1,0]
	v_pk_mul_f32 v[50:51], v[50:51], v[182:183] op_sel_hi:[1,0]
	v_pk_mul_f32 v[48:49], v[48:49], v[182:183] op_sel_hi:[1,0]
	v_pk_mul_f32 v[46:47], v[46:47], v[182:183] op_sel_hi:[1,0]
	v_pk_mul_f32 v[44:45], v[44:45], v[182:183] op_sel_hi:[1,0]
	v_pk_mul_f32 v[42:43], v[42:43], v[182:183] op_sel_hi:[1,0]
	v_pk_mul_f32 v[40:41], v[40:41], v[182:183] op_sel_hi:[1,0]
	v_pk_mul_f32 v[38:39], v[38:39], v[182:183] op_sel_hi:[1,0]
	v_pk_mul_f32 v[36:37], v[36:37], v[182:183] op_sel_hi:[1,0]
	v_pk_mul_f32 v[34:35], v[34:35], v[182:183] op_sel_hi:[1,0]
	v_pk_mul_f32 v[32:33], v[32:33], v[182:183] op_sel_hi:[1,0]
	v_mul_f32_e32 v185, v185, v182
	s_branch .LBB0_423

.LBB0_423:
	v_max_f32_e32 v181, v64, v64
	v_max_f32_e32 v182, v96, v96
	v_max_f32_e32 v181, v182, v181
	v_max3_f32 v182, v65, v98, v66
	v_max3_f32 v181, v181, v97, v99
	v_max3_f32 v182, v182, v100, v68
	v_max3_f32 v181, v181, v67, v101
	v_max3_f32 v182, v182, v102, v70
	v_max3_f32 v181, v181, v69, v103
	v_max3_f32 v182, v182, v104, v72
	v_max3_f32 v181, v181, v71, v105
	v_max3_f32 v182, v182, v106, v74
	v_max3_f32 v181, v181, v73, v107
	v_max3_f32 v182, v182, v108, v76
	v_max3_f32 v181, v181, v75, v109
	v_max3_f32 v182, v182, v110, v78
	v_max3_f32 v181, v181, v77, v111
	v_max3_f32 v181, v181, v79, v182
	v_mov_b32_e32 v182, v181
	s_waitcnt lgkmcnt(0)
	s_nop 1
	v_permlane32_swap_b32_e32 v181, v182
	v_max3_f32 v186, v184, v181, v182
	v_cmp_gt_f32_e32 vcc, v186, v184
	s_cbranch_vccz .LBB0_425
	v_sub_f32_e32 v181, v184, v186
	v_exp_f32_e32 v182, v181
	s_nop 0
	v_pk_mul_f32 v[30:31], v[30:31], v[182:183] op_sel_hi:[1,0]
	v_pk_mul_f32 v[28:29], v[28:29], v[182:183] op_sel_hi:[1,0]
	v_pk_mul_f32 v[26:27], v[26:27], v[182:183] op_sel_hi:[1,0]
	v_pk_mul_f32 v[24:25], v[24:25], v[182:183] op_sel_hi:[1,0]
	v_pk_mul_f32 v[22:23], v[22:23], v[182:183] op_sel_hi:[1,0]
	v_pk_mul_f32 v[20:21], v[20:21], v[182:183] op_sel_hi:[1,0]
	v_pk_mul_f32 v[18:19], v[18:19], v[182:183] op_sel_hi:[1,0]
	v_pk_mul_f32 v[16:17], v[16:17], v[182:183] op_sel_hi:[1,0]
	v_pk_mul_f32 v[14:15], v[14:15], v[182:183] op_sel_hi:[1,0]
	v_pk_mul_f32 v[12:13], v[12:13], v[182:183] op_sel_hi:[1,0]
	v_pk_mul_f32 v[10:11], v[10:11], v[182:183] op_sel_hi:[1,0]
	v_pk_mul_f32 v[8:9], v[8:9], v[182:183] op_sel_hi:[1,0]
	v_pk_mul_f32 v[6:7], v[6:7], v[182:183] op_sel_hi:[1,0]
	v_pk_mul_f32 v[4:5], v[4:5], v[182:183] op_sel_hi:[1,0]
	v_pk_mul_f32 v[2:3], v[2:3], v[182:183] op_sel_hi:[1,0]
	v_pk_mul_f32 v[0:1], v[0:1], v[182:183] op_sel_hi:[1,0]
	v_mul_f32_e32 v180, v180, v182
	s_branch .LBB0_426

; #define LAS __attribute__((address_space(3)))
; __device__ __forceinline__ unsigned pk2(float lo, float hi) { f32x2_t v = {lo, hi}; bf16x2_t b = __builtin_convertvector(v, bf16x2_t); return __builtin_bit_cast(unsigned, b); }
; template <int DK, bool IS_A>
; __device__ __forceinline__ void attn_unit(const Params& P, int l, LAS unsigned char* lds, int b, int grp, int qtok0, int nkeys) {
;     ...
;             AT_SOFTMAX(pa, ma, la, oa0, oa1);
;             AT_SOFTMAX(pb, mb, lb_, ob0, ob1);
;     ...
; #pragma unroll
;             for (int ks = 0; ks < 4; ++ks) {
;                 const int o8 = 8 * (ks & 1);
;                 u32x4 w; const f32x16& xa = pa[ks >> 1]; const f32x16& xb = pb[ks >> 1];
;                 w.x = pk2(xa[o8], xa[o8 + 1]); w.y = pk2(xa[o8 + 2], xa[o8 + 3]); w.z = pk2(xa[o8 + 4], xa[o8 + 5]); w.w = pk2(xa[o8 + 6], xa[o8 + 7]);
;                 const bf16x8 pfa = __builtin_bit_cast(bf16x8, w);
;                 w.x = pk2(xb[o8], xb[o8 + 1]); w.y = pk2(xb[o8 + 2], xb[o8 + 3]); w.z = pk2(xb[o8 + 4], xb[o8 + 5]); w.w = pk2(xb[o8 + 6], xb[o8 + 7]);
;                 const bf16x8 pfb = __builtin_bit_cast(bf16x8, w);
;                 const u32x2 a0 = *(const LAS u32x2*)(vb + ks * 32), a1 = *(const LAS u32x2*)(vb + ks * 32 + 16);
;                 const u32x2 c0 = *(const LAS u32x2*)(vb + 32 * AV_PITCH + ks * 32), c1 = *(const LAS u32x2*)(vb + 32 * AV_PITCH + ks * 32 + 16);
;                 const bf16x8 v0 = __builtin_bit_cast(bf16x8, ((u32x4){a0.x, a0.y, a1.x, a1.y})), v1 = __builtin_bit_cast(bf16x8, ((u32x4){c0.x, c0.y, c1.x, c1.y}));
;                 oa0 = __builtin_amdgcn_mfma_f32_32x32x16_bf16(v0, pfa, oa0, 0, 0, 0);
;                 oa1 = __builtin_amdgcn_mfma_f32_32x32x16_bf16(v1, pfa, oa1, 0, 0, 0);
;                 ob0 = __builtin_amdgcn_mfma_f32_32x32x16_bf16(v0, pfb, ob0, 0, 0, 0);
;                 ob1 = __builtin_amdgcn_mfma_f32_32x32x16_bf16(v1, pfb, ob1, 0, 0, 0);
;             }
.LBB0_426:
	v_sub_f32_e32 v112, v112, v188
	v_exp_f32_e32 v112, v112
	v_sub_f32_e32 v113, v113, v188
	v_exp_f32_e32 v113, v113
	v_sub_f32_e32 v114, v114, v188
	v_exp_f32_e32 v114, v114
	v_sub_f32_e32 v115, v115, v188
	v_exp_f32_e32 v115, v115
	v_sub_f32_e32 v116, v116, v188
	v_add_f32_e32 v181, 0, v112
	v_exp_f32_e32 v116, v116
	v_sub_f32_e32 v117, v117, v188
	v_add_f32_e32 v181, v113, v181
	v_exp_f32_e32 v117, v117
	v_sub_f32_e32 v118, v118, v188
	v_add_f32_e32 v181, v114, v181
	v_exp_f32_e32 v118, v118
	v_sub_f32_e32 v119, v119, v188
	v_add_f32_e32 v181, v115, v181
	v_exp_f32_e32 v119, v119
	v_sub_f32_e32 v120, v120, v188
	v_add_f32_e32 v181, v116, v181
	v_exp_f32_e32 v120, v120
	v_sub_f32_e32 v121, v121, v188
	v_add_f32_e32 v181, v117, v181
	v_exp_f32_e32 v121, v121
	v_sub_f32_e32 v122, v122, v188
	v_add_f32_e32 v181, v118, v181
	v_exp_f32_e32 v122, v122
	v_sub_f32_e32 v123, v123, v188
	v_add_f32_e32 v181, v119, v181
	v_exp_f32_e32 v123, v123
	v_sub_f32_e32 v124, v124, v188
	v_add_f32_e32 v181, v120, v181
	v_exp_f32_e32 v124, v124
	v_sub_f32_e32 v125, v125, v188
	v_add_f32_e32 v181, v121, v181
	v_exp_f32_e32 v125, v125
	v_sub_f32_e32 v126, v126, v188
	v_add_f32_e32 v181, v122, v181
	v_exp_f32_e32 v126, v126
	v_sub_f32_e32 v127, v127, v188
	v_add_f32_e32 v181, v123, v181
	v_exp_f32_e32 v127, v127
	v_sub_f32_e32 v80, v80, v188
	v_add_f32_e32 v181, v124, v181
	v_exp_f32_e32 v211, v80
	v_sub_f32_e32 v80, v81, v188
	v_add_f32_e32 v181, v125, v181
	v_exp_f32_e32 v212, v80
	v_sub_f32_e32 v81, v82, v188
	v_add_f32_e32 v80, v126, v181
	v_exp_f32_e32 v181, v81
	v_sub_f32_e32 v81, v83, v188
	v_add_f32_e32 v80, v127, v80
	v_exp_f32_e32 v213, v81
	v_sub_f32_e32 v81, v84, v188
	v_add_f32_e32 v80, v211, v80
	v_exp_f32_e32 v214, v81
	v_sub_f32_e32 v81, v85, v188
	v_add_f32_e32 v80, v212, v80
	v_exp_f32_e32 v215, v81
	v_sub_f32_e32 v81, v86, v188
	v_add_f32_e32 v80, v181, v80
	v_exp_f32_e32 v216, v81
	v_sub_f32_e32 v81, v87, v188
	v_add_f32_e32 v80, v213, v80
	v_exp_f32_e32 v217, v81
	v_sub_f32_e32 v81, v88, v188
	v_add_f32_e32 v80, v214, v80
	v_exp_f32_e32 v218, v81
	v_sub_f32_e32 v81, v89, v188
	v_add_f32_e32 v80, v215, v80
	v_exp_f32_e32 v220, v81
	v_add_f32_e32 v80, v216, v80
	v_add_f32_e32 v80, v217, v80
	v_add_f32_e32 v80, v218, v80
	v_add_f32_e32 v224, v220, v80
	v_sub_f32_e32 v80, v90, v188
	v_exp_f32_e32 v225, v80
	v_sub_f32_e32 v80, v91, v188
	v_exp_f32_e32 v226, v80
	v_sub_f32_e32 v80, v92, v188
	v_exp_f32_e32 v92, v80
	v_add_u32_e32 v80, s12, v178
	v_sub_f32_e32 v81, v96, v186
	v_add_u32_e32 v88, v80, v164
	v_exp_f32_e32 v184, v81
	v_sub_f32_e32 v81, v97, v186
	v_add_u32_e32 v182, 0x4800, v88
	v_add_u32_e32 v183, 0x6800, v88
	v_exp_f32_e32 v189, v81
	ds_read2_b64 v[80:83], v182 offset1:2
	ds_read2_b64 v[88:91], v183 offset0:32 offset1:34
	v_sub_f32_e32 v96, v99, v186
	v_sub_f32_e32 v84, v98, v186
	v_exp_f32_e32 v191, v96
	v_sub_f32_e32 v96, v100, v186
	v_exp_f32_e32 v190, v84
	v_cvt_pk_bf16_f32 v84, v112, v113
	v_cvt_pk_bf16_f32 v85, v114, v115
	v_cvt_pk_bf16_f32 v86, v116, v117
	v_cvt_pk_bf16_f32 v87, v118, v119
	v_exp_f32_e32 v192, v96
	v_sub_f32_e32 v96, v101, v186
	s_waitcnt lgkmcnt(1)
	v_mfma_f32_32x32x16_bf16 v[48:63], v[80:83], v[84:87], v[48:63]
	v_exp_f32_e32 v193, v96
	v_sub_f32_e32 v96, v102, v186
	v_exp_f32_e32 v194, v96
	v_sub_f32_e32 v96, v107, v186
	v_exp_f32_e32 v199, v96
	v_sub_f32_e32 v96, v108, v186
	v_exp_f32_e32 v204, v96
	s_waitcnt lgkmcnt(0)
	v_mfma_f32_32x32x16_bf16 v[32:47], v[88:91], v[84:87], v[32:47]
	v_sub_f32_e32 v84, v103, v186
	v_exp_f32_e32 v195, v84
	v_cvt_pk_bf16_f32 v84, v184, v189
	v_cvt_pk_bf16_f32 v85, v190, v191
	v_cvt_pk_bf16_f32 v86, v192, v193
	v_cvt_pk_bf16_f32 v87, v194, v195
	v_sub_f32_e32 v96, v109, v186
	v_exp_f32_e32 v205, v96
	v_mfma_f32_32x32x16_bf16 v[16:31], v[80:83], v[84:87], v[16:31]
	v_sub_f32_e32 v80, v93, v188
	v_exp_f32_e32 v93, v80
	v_sub_f32_e32 v80, v104, v186
	v_exp_f32_e32 v196, v80
	v_sub_f32_e32 v80, v105, v186
	v_exp_f32_e32 v197, v80
	ds_read2_b64 v[80:83], v182 offset0:4 offset1:6
	v_mfma_f32_32x32x16_bf16 v[0:15], v[88:91], v[84:87], v[0:15]
	ds_read2_b64 v[88:91], v183 offset0:36 offset1:38
	v_sub_f32_e32 v84, v106, v186
	v_exp_f32_e32 v198, v84
	v_cvt_pk_bf16_f32 v84, v120, v121
	v_cvt_pk_bf16_f32 v85, v122, v123
	v_cvt_pk_bf16_f32 v86, v124, v125
	v_cvt_pk_bf16_f32 v87, v126, v127
	v_sub_f32_e32 v96, v110, v186
	v_exp_f32_e32 v206, v96
	s_waitcnt lgkmcnt(1)
	v_mfma_f32_32x32x16_bf16 v[48:63], v[80:83], v[84:87], v[48:63]
	v_sub_f32_e32 v64, v64, v186
	v_exp_f32_e32 v208, v64
	v_sub_f32_e32 v64, v65, v186
	v_exp_f32_e32 v209, v64
	v_sub_f32_e32 v64, v66, v186
	v_exp_f32_e32 v210, v64
	v_sub_f32_e32 v64, v67, v186
	s_waitcnt lgkmcnt(0)
; #define LAS __attribute__((address_space(3)))
; __device__ __forceinline__ unsigned pk2(float lo, float hi) { f32x2_t v = {lo, hi}; bf16x2_t b = __builtin_convertvector(v, bf16x2_t); return __builtin_bit_cast(unsigned, b); }
; template <int DK, bool IS_A>
; __device__ __forceinline__ void attn_unit(const Params& P, int l, LAS unsigned char* lds, int b, int grp, int qtok0, int nkeys) {
;     ...
;             __builtin_amdgcn_s_setprio(1);
; #pragma unroll
;             for (int i = 0; i < DK / 16; ++i)
; #pragma unroll
;                 for (int jj = 0; jj < 2; ++jj) {
;                     const bf16x8 kf = *(const LAS bf16x8*)(kb + jj * 32 * AK_PITCH + i * 32);
;                     pa[jj] = __builtin_amdgcn_mfma_f32_32x32x16_bf16(kf, qa[i], pa[jj], 0, 0, 0);
;                     pb[jj] = __builtin_amdgcn_mfma_f32_32x32x16_bf16(kf, qb[i], pb[jj], 0, 0, 0);
;                 }
;             __builtin_amdgcn_s_setprio(0);
;     ...
;             for (int ks = 0; ks < 4; ++ks) {
;                 const int o8 = 8 * (ks & 1);
;                 u32x4 w; const f32x16& xa = pa[ks >> 1]; const f32x16& xb = pb[ks >> 1];
;                 w.x = pk2(xa[o8], xa[o8 + 1]); w.y = pk2(xa[o8 + 2], xa[o8 + 3]); w.z = pk2(xa[o8 + 4], xa[o8 + 5]); w.w = pk2(xa[o8 + 6], xa[o8 + 7]);
;                 const bf16x8 pfa = __builtin_bit_cast(bf16x8, w);
;                 w.x = pk2(xb[o8], xb[o8 + 1]); w.y = pk2(xb[o8 + 2], xb[o8 + 3]); w.z = pk2(xb[o8 + 4], xb[o8 + 5]); w.w = pk2(xb[o8 + 6], xb[o8 + 7]);
;                 const bf16x8 pfb = __builtin_bit_cast(bf16x8, w);
;                 const u32x2 a0 = *(const LAS u32x2*)(vb + ks * 32), a1 = *(const LAS u32x2*)(vb + ks * 32 + 16);
;                 const u32x2 c0 = *(const LAS u32x2*)(vb + 32 * AV_PITCH + ks * 32), c1 = *(const LAS u32x2*)(vb + 32 * AV_PITCH + ks * 32 + 16);
;                 const bf16x8 v0 = __builtin_bit_cast(bf16x8, ((u32x4){a0.x, a0.y, a1.x, a1.y})), v1 = __builtin_bit_cast(bf16x8, ((u32x4){c0.x, c0.y, c1.x, c1.y}));
;                 oa0 = __builtin_amdgcn_mfma_f32_32x32x16_bf16(v0, pfa, oa0, 0, 0, 0);
;                 oa1 = __builtin_amdgcn_mfma_f32_32x32x16_bf16(v1, pfa, oa1, 0, 0, 0);
;                 ob0 = __builtin_amdgcn_mfma_f32_32x32x16_bf16(v0, pfb, ob0, 0, 0, 0);
;                 ob1 = __builtin_amdgcn_mfma_f32_32x32x16_bf16(v1, pfb, ob1, 0, 0, 0);
;             }
	v_mfma_f32_32x32x16_bf16 v[32:47], v[88:91], v[84:87], v[32:47]
	v_sub_f32_e32 v84, v111, v186
	v_exp_f32_e32 v207, v84
	v_cvt_pk_bf16_f32 v84, v196, v197
	v_cvt_pk_bf16_f32 v85, v198, v199
	v_cvt_pk_bf16_f32 v86, v204, v205
	v_cvt_pk_bf16_f32 v87, v206, v207
	s_nop 1
	v_mfma_f32_32x32x16_bf16 v[16:31], v[80:83], v[84:87], v[16:31]
	v_sub_f32_e32 v80, v94, v188
	v_exp_f32_e32 v94, v80
	ds_read2_b64 v[80:83], v182 offset0:8 offset1:10
	v_mfma_f32_32x32x16_bf16 v[0:15], v[88:91], v[84:87], v[0:15]
	ds_read2_b64 v[88:91], v183 offset0:40 offset1:42
	v_cvt_pk_bf16_f32 v84, v211, v212
	v_exp_f32_e32 v211, v64
	v_sub_f32_e32 v64, v68, v186
	v_exp_f32_e32 v212, v64
	v_sub_f32_e32 v64, v69, v186
	v_cvt_pk_bf16_f32 v85, v181, v213
	v_exp_f32_e32 v213, v64
	v_sub_f32_e32 v64, v70, v186
	v_cvt_pk_bf16_f32 v86, v214, v215
	v_exp_f32_e32 v214, v64
	v_sub_f32_e32 v64, v71, v186
	v_exp_f32_e32 v215, v64
	v_cvt_pk_bf16_f32 v87, v216, v217
	v_sub_f32_e32 v68, v95, v188
	v_cvt_pk_bf16_f32 v64, v208, v209
	s_waitcnt lgkmcnt(1)
	v_mfma_f32_32x32x16_bf16 v[48:63], v[80:83], v[84:87], v[48:63]
	v_cvt_pk_bf16_f32 v65, v210, v211
	v_cvt_pk_bf16_f32 v66, v212, v213
	v_cvt_pk_bf16_f32 v67, v214, v215
	s_waitcnt lgkmcnt(0)
	v_mfma_f32_32x32x16_bf16 v[32:47], v[88:91], v[84:87], v[32:47]
	v_exp_f32_e32 v84, v68
	v_sub_f32_e32 v68, v72, v186
	v_exp_f32_e32 v216, v68
	v_sub_f32_e32 v68, v73, v186
	v_exp_f32_e32 v217, v68
	ds_read2_b64 v[68:71], v182 offset0:12 offset1:14
	v_sub_f32_e32 v72, v75, v186
	v_mfma_f32_32x32x16_bf16 v[16:31], v[80:83], v[64:67], v[16:31]
	ds_read2_b64 v[80:83], v183 offset0:44 offset1:46
	v_exp_f32_e32 v222, v72
	v_sub_f32_e32 v72, v76, v186
	v_exp_f32_e32 v223, v72
	v_sub_f32_e32 v72, v77, v186
	v_mfma_f32_32x32x16_bf16 v[0:15], v[88:91], v[64:67], v[0:15]
	v_sub_f32_e32 v64, v74, v186
	v_exp_f32_e32 v219, v64
	v_cvt_pk_bf16_f32 v64, v218, v220
	v_cvt_pk_bf16_f32 v65, v225, v226
	v_cvt_pk_bf16_f32 v66, v92, v93
	v_cvt_pk_bf16_f32 v67, v94, v84
	v_exp_f32_e32 v218, v72
	v_sub_f32_e32 v72, v78, v186
	s_waitcnt lgkmcnt(1)
	v_mfma_f32_32x32x16_bf16 v[48:63], v[68:71], v[64:67], v[48:63]
	v_exp_f32_e32 v220, v72
	s_waitcnt lgkmcnt(0)
	v_mfma_f32_32x32x16_bf16 v[32:47], v[80:83], v[64:67], v[32:47]
	v_sub_f32_e32 v64, v79, v186
	v_exp_f32_e32 v221, v64
	v_cvt_pk_bf16_f32 v64, v216, v217
	v_cvt_pk_bf16_f32 v65, v219, v222
	v_cvt_pk_bf16_f32 v66, v223, v218
	v_cvt_pk_bf16_f32 v67, v220, v221
	s_nop 1
	v_mfma_f32_32x32x16_bf16 v[16:31], v[68:71], v[64:67], v[16:31]
	v_add_f32_e32 v68, v225, v224
	v_add_f32_e32 v68, v226, v68
	v_add_f32_e32 v68, v92, v68
	v_add_f32_e32 v68, v93, v68
	v_add_f32_e32 v68, v94, v68
	v_add_f32_e32 v68, v84, v68
	v_add_f32_e32 v185, v185, v68
	v_mfma_f32_32x32x16_bf16 v[0:15], v[80:83], v[64:67], v[0:15]
	s_setprio 1
	ds_read_b128 v[64:67], v187 offset:9216
	ds_read_b128 v[224:227], v187 offset:9248
	s_waitcnt lgkmcnt(1)
	v_mfma_f32_32x32x16_bf16 v[112:127], v[64:67], v[138:141], 0
	v_mfma_f32_32x32x16_bf16 v[96:111], v[64:67], v[146:149], 0
	ds_read_b128 v[64:67], v187 offset:13824
	s_waitcnt lgkmcnt(1)
	v_mfma_f32_32x32x16_bf16 v[112:127], v[224:227], v[142:145], v[112:127]
	v_mfma_f32_32x32x16_bf16 v[96:111], v[224:227], v[150:153], v[96:111]
	ds_read_b128 v[224:227], v187 offset:13856
	s_waitcnt lgkmcnt(1)
	v_mfma_f32_32x32x16_bf16 v[80:95], v[64:67], v[138:141], 0
	v_mfma_f32_32x32x16_bf16 v[64:79], v[64:67], v[146:149], 0
	s_waitcnt lgkmcnt(0)
	v_mfma_f32_32x32x16_bf16 v[80:95], v[224:227], v[142:145], v[80:95]
	v_mfma_f32_32x32x16_bf16 v[64:79], v[224:227], v[150:153], v[64:79]
	s_setprio 0
	s_nop 9
	v_max_f32_e32 v181, v80, v80
	v_max_f32_e32 v187, v112, v112
	v_max_f32_e32 v181, v187, v181
	v_max3_f32 v187, v81, v114, v82
	v_max3_f32 v181, v181, v113, v115
	v_max3_f32 v187, v187, v116, v84
	v_max3_f32 v181, v181, v83, v117
	v_max3_f32 v187, v187, v118, v86
	v_max3_f32 v181, v181, v85, v119
	v_max3_f32 v187, v187, v120, v88
	v_max3_f32 v181, v181, v87, v121
	v_max3_f32 v187, v187, v122, v90
	v_max3_f32 v181, v181, v89, v123
	v_max3_f32 v187, v187, v124, v92
	v_max3_f32 v181, v181, v91, v125
	v_max3_f32 v187, v187, v126, v94
	v_max3_f32 v181, v181, v93, v127
	v_max3_f32 v181, v181, v95, v187
	v_mov_b32_e32 v187, v181
	s_waitcnt lgkmcnt(0)
	s_nop 1
	v_permlane32_swap_b32_e32 v181, v187
	v_max3_f32 v181, v188, v181, v187
	v_cmp_gt_f32_e32 vcc, v181, v188
	s_cbranch_vccz .LBB0_428
	v_sub_f32_e32 v187, v188, v181
	v_exp_f32_e32 v188, v187
	s_nop 0
	v_pk_mul_f32 v[62:63], v[62:63], v[188:189] op_sel_hi:[1,0]
	v_pk_mul_f32 v[60:61], v[60:61], v[188:189] op_sel_hi:[1,0]
	v_pk_mul_f32 v[58:59], v[58:59], v[188:189] op_sel_hi:[1,0]
	v_pk_mul_f32 v[56:57], v[56:57], v[188:189] op_sel_hi:[1,0]
	v_pk_mul_f32 v[54:55], v[54:55], v[188:189] op_sel_hi:[1,0]
	v_pk_mul_f32 v[52:53], v[52:53], v[188:189] op_sel_hi:[1,0]
	v_pk_mul_f32 v[50:51], v[50:51], v[188:189] op_sel_hi:[1,0]
	v_pk_mul_f32 v[48:49], v[48:49], v[188:189] op_sel_hi:[1,0]
	v_pk_mul_f32 v[46:47], v[46:47], v[188:189] op_sel_hi:[1,0]
	v_pk_mul_f32 v[44:45], v[44:45], v[188:189] op_sel_hi:[1,0]
	v_pk_mul_f32 v[42:43], v[42:43], v[188:189] op_sel_hi:[1,0]
	v_pk_mul_f32 v[40:41], v[40:41], v[188:189] op_sel_hi:[1,0]
	v_pk_mul_f32 v[38:39], v[38:39], v[188:189] op_sel_hi:[1,0]
	v_pk_mul_f32 v[36:37], v[36:37], v[188:189] op_sel_hi:[1,0]
	v_pk_mul_f32 v[34:35], v[34:35], v[188:189] op_sel_hi:[1,0]
	v_pk_mul_f32 v[32:33], v[32:33], v[188:189] op_sel_hi:[1,0]
	v_mul_f32_e32 v185, v185, v188
	s_branch .LBB0_429

.LBB0_429:
	v_add_f32_e32 v184, 0, v184
	v_add_f32_e32 v184, v189, v184
	v_add_f32_e32 v184, v190, v184
	v_add_f32_e32 v184, v191, v184
	v_add_f32_e32 v184, v192, v184
	v_add_f32_e32 v184, v193, v184
	v_add_f32_e32 v184, v194, v184
	v_add_f32_e32 v184, v195, v184
	v_add_f32_e32 v184, v196, v184
	v_add_f32_e32 v184, v197, v184
	v_add_f32_e32 v184, v198, v184
	v_add_f32_e32 v184, v199, v184
	v_add_f32_e32 v184, v204, v184
	v_add_f32_e32 v184, v205, v184
	v_add_f32_e32 v184, v206, v184
	v_add_f32_e32 v184, v207, v184
	v_add_f32_e32 v184, v208, v184
	v_add_f32_e32 v184, v209, v184
	v_max_f32_e32 v187, v64, v64
	v_max_f32_e32 v188, v96, v96
	v_add_f32_e32 v184, v210, v184
	v_max_f32_e32 v187, v188, v187
	v_add_f32_e32 v184, v211, v184
	v_max3_f32 v188, v65, v98, v66
	v_max3_f32 v187, v187, v97, v99
	v_add_f32_e32 v184, v212, v184
	v_max3_f32 v188, v188, v100, v68
	v_max3_f32 v187, v187, v67, v101
	v_add_f32_e32 v184, v213, v184
	v_max3_f32 v188, v188, v102, v70
	v_max3_f32 v187, v187, v69, v103
	v_add_f32_e32 v184, v214, v184
	v_max3_f32 v188, v188, v104, v72
	v_max3_f32 v187, v187, v71, v105
	v_add_f32_e32 v184, v215, v184
	v_max3_f32 v188, v188, v106, v74
	v_max3_f32 v187, v187, v73, v107
	v_add_f32_e32 v184, v216, v184
	v_max3_f32 v188, v188, v108, v76
	v_max3_f32 v187, v187, v75, v109
	v_add_f32_e32 v184, v217, v184
	v_max3_f32 v188, v188, v110, v78
	v_max3_f32 v187, v187, v77, v111
	v_add_f32_e32 v184, v219, v184
	v_max3_f32 v187, v187, v79, v188
	v_add_f32_e32 v184, v222, v184
	v_mov_b32_e32 v188, v187
	v_add_f32_e32 v184, v223, v184
	v_add_f32_e32 v184, v218, v184
	v_add_f32_e32 v184, v220, v184
	v_add_f32_e32 v184, v221, v184
	v_add_f32_e32 v180, v180, v184
	s_waitcnt lgkmcnt(0)
	v_permlane32_swap_b32_e32 v187, v188
	v_max3_f32 v184, v186, v187, v188
	v_cmp_gt_f32_e32 vcc, v184, v186
	s_cbranch_vccz .LBB0_431
	v_sub_f32_e32 v186, v186, v184
	v_exp_f32_e32 v186, v186
	s_nop 0
	v_pk_mul_f32 v[30:31], v[30:31], v[186:187] op_sel_hi:[1,0]
	v_pk_mul_f32 v[28:29], v[28:29], v[186:187] op_sel_hi:[1,0]
	v_pk_mul_f32 v[26:27], v[26:27], v[186:187] op_sel_hi:[1,0]
	v_pk_mul_f32 v[24:25], v[24:25], v[186:187] op_sel_hi:[1,0]
	v_pk_mul_f32 v[22:23], v[22:23], v[186:187] op_sel_hi:[1,0]
	v_pk_mul_f32 v[20:21], v[20:21], v[186:187] op_sel_hi:[1,0]
	v_pk_mul_f32 v[18:19], v[18:19], v[186:187] op_sel_hi:[1,0]
	v_pk_mul_f32 v[16:17], v[16:17], v[186:187] op_sel_hi:[1,0]
	v_pk_mul_f32 v[14:15], v[14:15], v[186:187] op_sel_hi:[1,0]
	v_pk_mul_f32 v[12:13], v[12:13], v[186:187] op_sel_hi:[1,0]
	v_pk_mul_f32 v[10:11], v[10:11], v[186:187] op_sel_hi:[1,0]
	v_pk_mul_f32 v[8:9], v[8:9], v[186:187] op_sel_hi:[1,0]
	v_pk_mul_f32 v[6:7], v[6:7], v[186:187] op_sel_hi:[1,0]
	v_pk_mul_f32 v[4:5], v[4:5], v[186:187] op_sel_hi:[1,0]
	v_pk_mul_f32 v[2:3], v[2:3], v[186:187] op_sel_hi:[1,0]
	v_pk_mul_f32 v[0:1], v[0:1], v[186:187] op_sel_hi:[1,0]
	v_mul_f32_e32 v180, v180, v186
	s_branch .LBB0_432

; #define LAS __attribute__((address_space(3)))
; template <int DK, bool IS_A>
; __device__ __forceinline__ void attn_unit(const Params& P, int l, LAS unsigned char* lds, int b, int grp, int qtok0, int nkeys) {
;     ...
;         for (int h = 0; h < 2; ++h) {
;             const LAS unsigned char* kb = lds + buf * A_BUF + kfo + h * 64 * AK_PITCH;
;             const LAS unsigned char* vb = lds + buf * A_BUF + vfo + h * 128;
;             f32x16 pa[2], pb[2];
; #pragma unroll
;             for (int jj = 0; jj < 2; ++jj)
; #pragma unroll
;                 for (int r = 0; r < 16; ++r) { pa[jj][r] = 0.f; pb[jj][r] = 0.f; }
;             __builtin_amdgcn_s_setprio(1);
; #pragma unroll
;             for (int i = 0; i < DK / 16; ++i)
; #pragma unroll
;                 for (int jj = 0; jj < 2; ++jj) {
;                     const bf16x8 kf = *(const LAS bf16x8*)(kb + jj * 32 * AK_PITCH + i * 32);
;                     pa[jj] = __builtin_amdgcn_mfma_f32_32x32x16_bf16(kf, qa[i], pa[jj], 0, 0, 0);
;                     pb[jj] = __builtin_amdgcn_mfma_f32_32x32x16_bf16(kf, qb[i], pb[jj], 0, 0, 0);
;                 }
;             __builtin_amdgcn_s_setprio(0);
.LBB0_445:
	s_mov_b32 s12, s100
	v_add_u32_e32 v64, s12, v178
	v_add_u32_e32 v199, v64, v192
	s_setprio 1
	ds_read_b128 v[64:67], v199
	ds_read_b128 v[204:207], v199 offset:32
	s_waitcnt lgkmcnt(1)
	v_mfma_f32_32x32x16_bf16 v[112:127], v[64:67], v[142:145], 0
	v_mfma_f32_32x32x16_bf16 v[96:111], v[64:67], v[146:149], 0
	ds_read_b128 v[64:67], v199 offset:4608
	s_waitcnt lgkmcnt(1)
	v_mfma_f32_32x32x16_bf16 v[112:127], v[204:207], v[154:157], v[112:127]
	v_mfma_f32_32x32x16_bf16 v[96:111], v[204:207], v[162:165], v[96:111]
	ds_read_b128 v[204:207], v199 offset:4640
	s_waitcnt lgkmcnt(1)
	v_mfma_f32_32x32x16_bf16 v[80:95], v[64:67], v[142:145], 0
	v_mfma_f32_32x32x16_bf16 v[64:79], v[64:67], v[146:149], 0
	s_waitcnt lgkmcnt(0)
	v_mfma_f32_32x32x16_bf16 v[80:95], v[204:207], v[154:157], v[80:95]
	v_mfma_f32_32x32x16_bf16 v[64:79], v[204:207], v[162:165], v[64:79]
	ds_read_b128 v[204:207], v199 offset:64
	s_waitcnt lgkmcnt(0)
	v_mfma_f32_32x32x16_bf16 v[112:127], v[204:207], v[158:161], v[112:127]
	v_mfma_f32_32x32x16_bf16 v[96:111], v[204:207], v[170:173], v[96:111]
	ds_read_b128 v[204:207], v199 offset:4672
	s_waitcnt lgkmcnt(0)
	v_mfma_f32_32x32x16_bf16 v[80:95], v[204:207], v[158:161], v[80:95]
	v_mfma_f32_32x32x16_bf16 v[64:79], v[204:207], v[170:173], v[64:79]
	ds_read_b128 v[204:207], v199 offset:96
	s_waitcnt lgkmcnt(0)
	v_mfma_f32_32x32x16_bf16 v[112:127], v[204:207], v[166:169], v[112:127]
	v_mfma_f32_32x32x16_bf16 v[96:111], v[204:207], v[174:177], v[96:111]
	ds_read_b128 v[204:207], v199 offset:4704
	s_waitcnt lgkmcnt(0)
	v_mfma_f32_32x32x16_bf16 v[80:95], v[204:207], v[166:169], v[80:95]
	v_mfma_f32_32x32x16_bf16 v[64:79], v[204:207], v[174:177], v[64:79]
	s_setprio 0
	s_nop 9
	v_max_f32_e32 v185, v80, v80
	v_max_f32_e32 v187, v112, v112
	v_max_f32_e32 v185, v187, v185
	v_max3_f32 v187, v81, v114, v82
	v_max3_f32 v185, v185, v113, v115
	v_max3_f32 v187, v187, v116, v84
	v_max3_f32 v185, v185, v83, v117
	v_max3_f32 v187, v187, v118, v86
	v_max3_f32 v185, v185, v85, v119
	v_max3_f32 v187, v187, v120, v88
	v_max3_f32 v185, v185, v87, v121
	v_max3_f32 v187, v187, v122, v90
	v_max3_f32 v185, v185, v89, v123
	v_max3_f32 v187, v187, v124, v92
	v_max3_f32 v185, v185, v91, v125
	v_max3_f32 v187, v187, v126, v94
	v_max3_f32 v185, v185, v93, v127
	v_max3_f32 v185, v185, v95, v187
	v_mov_b32_e32 v187, v185
	s_waitcnt lgkmcnt(0)
	s_nop 1
	v_permlane32_swap_b32_e32 v185, v187
	v_max3_f32 v205, v184, v185, v187
	v_cmp_gt_f32_e32 vcc, v205, v184
	s_cbranch_vccz .LBB0_447
	v_sub_f32_e32 v184, v184, v205
	v_exp_f32_e32 v184, v184
	s_nop 0
	v_pk_mul_f32 v[62:63], v[62:63], v[184:185] op_sel_hi:[1,0]
	v_pk_mul_f32 v[60:61], v[60:61], v[184:185] op_sel_hi:[1,0]
	v_pk_mul_f32 v[58:59], v[58:59], v[184:185] op_sel_hi:[1,0]
	v_pk_mul_f32 v[56:57], v[56:57], v[184:185] op_sel_hi:[1,0]
	v_pk_mul_f32 v[54:55], v[54:55], v[184:185] op_sel_hi:[1,0]
	v_pk_mul_f32 v[52:53], v[52:53], v[184:185] op_sel_hi:[1,0]
	v_pk_mul_f32 v[50:51], v[50:51], v[184:185] op_sel_hi:[1,0]
	v_pk_mul_f32 v[48:49], v[48:49], v[184:185] op_sel_hi:[1,0]
	v_pk_mul_f32 v[46:47], v[46:47], v[184:185] op_sel_hi:[1,0]
	v_pk_mul_f32 v[44:45], v[44:45], v[184:185] op_sel_hi:[1,0]
	v_pk_mul_f32 v[42:43], v[42:43], v[184:185] op_sel_hi:[1,0]
	v_pk_mul_f32 v[40:41], v[40:41], v[184:185] op_sel_hi:[1,0]
	v_pk_mul_f32 v[38:39], v[38:39], v[184:185] op_sel_hi:[1,0]
	v_pk_mul_f32 v[36:37], v[36:37], v[184:185] op_sel_hi:[1,0]
	v_pk_mul_f32 v[34:35], v[34:35], v[184:185] op_sel_hi:[1,0]
	v_pk_mul_f32 v[32:33], v[32:33], v[184:185] op_sel_hi:[1,0]
	v_mul_f32_e32 v198, v198, v184
	s_branch .LBB0_448

.LBB0_448:
	v_max_f32_e32 v184, v64, v64
	v_max_f32_e32 v185, v96, v96
	v_max_f32_e32 v184, v185, v184
	v_max3_f32 v185, v65, v98, v66
	v_max3_f32 v184, v184, v97, v99
	v_max3_f32 v185, v185, v100, v68
	v_max3_f32 v184, v184, v67, v101
	v_max3_f32 v185, v185, v102, v70
	v_max3_f32 v184, v184, v69, v103
	v_max3_f32 v185, v185, v104, v72
	v_max3_f32 v184, v184, v71, v105
	v_max3_f32 v185, v185, v106, v74
	v_max3_f32 v184, v184, v73, v107
	v_max3_f32 v185, v185, v108, v76
	v_max3_f32 v184, v184, v75, v109
	v_max3_f32 v185, v185, v110, v78
	v_max3_f32 v184, v184, v77, v111
	v_max3_f32 v184, v184, v79, v185
	v_mov_b32_e32 v185, v184
	s_waitcnt lgkmcnt(0)
	s_nop 1
	v_permlane32_swap_b32_e32 v184, v185
	v_max3_f32 v204, v193, v184, v185
	v_cmp_gt_f32_e32 vcc, v204, v193
	s_cbranch_vccz .LBB0_450
	v_sub_f32_e32 v184, v193, v204
	v_exp_f32_e32 v184, v184
	s_nop 0
	v_pk_mul_f32 v[30:31], v[30:31], v[184:185] op_sel_hi:[1,0]
	v_pk_mul_f32 v[28:29], v[28:29], v[184:185] op_sel_hi:[1,0]
	v_pk_mul_f32 v[26:27], v[26:27], v[184:185] op_sel_hi:[1,0]
	v_pk_mul_f32 v[24:25], v[24:25], v[184:185] op_sel_hi:[1,0]
	v_pk_mul_f32 v[22:23], v[22:23], v[184:185] op_sel_hi:[1,0]
	v_pk_mul_f32 v[20:21], v[20:21], v[184:185] op_sel_hi:[1,0]
	v_pk_mul_f32 v[18:19], v[18:19], v[184:185] op_sel_hi:[1,0]
	v_pk_mul_f32 v[16:17], v[16:17], v[184:185] op_sel_hi:[1,0]
	v_pk_mul_f32 v[14:15], v[14:15], v[184:185] op_sel_hi:[1,0]
	v_pk_mul_f32 v[12:13], v[12:13], v[184:185] op_sel_hi:[1,0]
	v_pk_mul_f32 v[10:11], v[10:11], v[184:185] op_sel_hi:[1,0]
	v_pk_mul_f32 v[8:9], v[8:9], v[184:185] op_sel_hi:[1,0]
	v_pk_mul_f32 v[6:7], v[6:7], v[184:185] op_sel_hi:[1,0]
	v_pk_mul_f32 v[4:5], v[4:5], v[184:185] op_sel_hi:[1,0]
	v_pk_mul_f32 v[2:3], v[2:3], v[184:185] op_sel_hi:[1,0]
	v_pk_mul_f32 v[0:1], v[0:1], v[184:185] op_sel_hi:[1,0]
	v_mul_f32_e32 v183, v183, v184
	s_branch .LBB0_451

; #define LAS __attribute__((address_space(3)))
; __device__ __forceinline__ unsigned pk2(float lo, float hi) { f32x2_t v = {lo, hi}; bf16x2_t b = __builtin_convertvector(v, bf16x2_t); return __builtin_bit_cast(unsigned, b); }
; template <int DK, bool IS_A>
; __device__ __forceinline__ void attn_unit(const Params& P, int l, LAS unsigned char* lds, int b, int grp, int qtok0, int nkeys) {
;     ...
;             AT_SOFTMAX(pa, ma, la, oa0, oa1);
;             AT_SOFTMAX(pb, mb, lb_, ob0, ob1);
;     ...
; #pragma unroll
;             for (int ks = 0; ks < 4; ++ks) {
;                 const int o8 = 8 * (ks & 1);
;                 u32x4 w; const f32x16& xa = pa[ks >> 1]; const f32x16& xb = pb[ks >> 1];
;                 w.x = pk2(xa[o8], xa[o8 + 1]); w.y = pk2(xa[o8 + 2], xa[o8 + 3]); w.z = pk2(xa[o8 + 4], xa[o8 + 5]); w.w = pk2(xa[o8 + 6], xa[o8 + 7]);
;                 const bf16x8 pfa = __builtin_bit_cast(bf16x8, w);
;                 w.x = pk2(xb[o8], xb[o8 + 1]); w.y = pk2(xb[o8 + 2], xb[o8 + 3]); w.z = pk2(xb[o8 + 4], xb[o8 + 5]); w.w = pk2(xb[o8 + 6], xb[o8 + 7]);
;                 const bf16x8 pfb = __builtin_bit_cast(bf16x8, w);
;                 const u32x2 a0 = *(const LAS u32x2*)(vb + ks * 32), a1 = *(const LAS u32x2*)(vb + ks * 32 + 16);
;                 const u32x2 c0 = *(const LAS u32x2*)(vb + 32 * AV_PITCH + ks * 32), c1 = *(const LAS u32x2*)(vb + 32 * AV_PITCH + ks * 32 + 16);
;                 const bf16x8 v0 = __builtin_bit_cast(bf16x8, ((u32x4){a0.x, a0.y, a1.x, a1.y})), v1 = __builtin_bit_cast(bf16x8, ((u32x4){c0.x, c0.y, c1.x, c1.y}));
;                 oa0 = __builtin_amdgcn_mfma_f32_32x32x16_bf16(v0, pfa, oa0, 0, 0, 0);
;                 oa1 = __builtin_amdgcn_mfma_f32_32x32x16_bf16(v1, pfa, oa1, 0, 0, 0);
;                 ob0 = __builtin_amdgcn_mfma_f32_32x32x16_bf16(v0, pfb, ob0, 0, 0, 0);
;                 ob1 = __builtin_amdgcn_mfma_f32_32x32x16_bf16(v1, pfb, ob1, 0, 0, 0);
;             }
.LBB0_451:
	v_sub_f32_e32 v112, v112, v205
	v_exp_f32_e32 v112, v112
	v_sub_f32_e32 v113, v113, v205
	v_exp_f32_e32 v113, v113
	v_sub_f32_e32 v114, v114, v205
	v_exp_f32_e32 v114, v114
	v_sub_f32_e32 v115, v115, v205
	v_exp_f32_e32 v115, v115
	v_sub_f32_e32 v116, v116, v205
	v_add_f32_e32 v184, 0, v112
	v_exp_f32_e32 v116, v116
	v_sub_f32_e32 v117, v117, v205
	v_add_f32_e32 v184, v113, v184
	v_exp_f32_e32 v117, v117
	v_sub_f32_e32 v118, v118, v205
	v_add_f32_e32 v184, v114, v184
	v_exp_f32_e32 v118, v118
	v_sub_f32_e32 v119, v119, v205
	v_add_f32_e32 v184, v115, v184
	v_exp_f32_e32 v119, v119
	v_sub_f32_e32 v120, v120, v205
	v_add_f32_e32 v184, v116, v184
	v_exp_f32_e32 v120, v120
	v_sub_f32_e32 v121, v121, v205
	v_add_f32_e32 v184, v117, v184
	v_exp_f32_e32 v121, v121
	v_sub_f32_e32 v122, v122, v205
	v_add_f32_e32 v184, v118, v184
	v_exp_f32_e32 v122, v122
	v_sub_f32_e32 v123, v123, v205
	v_add_f32_e32 v184, v119, v184
	v_exp_f32_e32 v123, v123
	v_sub_f32_e32 v124, v124, v205
	v_add_f32_e32 v184, v120, v184
	v_exp_f32_e32 v124, v124
	v_sub_f32_e32 v125, v125, v205
	v_add_f32_e32 v184, v121, v184
	v_exp_f32_e32 v125, v125
	v_sub_f32_e32 v126, v126, v205
	v_add_f32_e32 v184, v122, v184
	v_exp_f32_e32 v126, v126
	v_sub_f32_e32 v127, v127, v205
	v_add_f32_e32 v184, v123, v184
	v_exp_f32_e32 v127, v127
	v_sub_f32_e32 v80, v80, v205
	v_add_f32_e32 v184, v124, v184
	v_exp_f32_e32 v224, v80
	v_sub_f32_e32 v80, v81, v205
	v_add_f32_e32 v184, v125, v184
	v_exp_f32_e32 v225, v80
	v_sub_f32_e32 v81, v82, v205
	v_add_f32_e32 v80, v126, v184
	v_exp_f32_e32 v184, v81
	v_sub_f32_e32 v81, v83, v205
	v_add_f32_e32 v80, v127, v80
	v_exp_f32_e32 v226, v81
	v_sub_f32_e32 v81, v84, v205
	v_add_f32_e32 v80, v224, v80
	v_exp_f32_e32 v227, v81
	v_sub_f32_e32 v81, v85, v205
	v_add_f32_e32 v80, v225, v80
	v_exp_f32_e32 v228, v81
	v_sub_f32_e32 v81, v86, v205
	v_add_f32_e32 v80, v184, v80
	v_exp_f32_e32 v229, v81
	v_sub_f32_e32 v81, v87, v205
	v_add_f32_e32 v80, v226, v80
	v_exp_f32_e32 v230, v81
	v_sub_f32_e32 v81, v88, v205
	v_add_f32_e32 v80, v227, v80
	v_exp_f32_e32 v231, v81
	v_sub_f32_e32 v81, v89, v205
	v_add_f32_e32 v80, v228, v80
	v_exp_f32_e32 v233, v81
	v_add_f32_e32 v80, v229, v80
	v_add_f32_e32 v80, v230, v80
	v_add_f32_e32 v80, v231, v80
	v_add_f32_e32 v237, v233, v80
	v_sub_f32_e32 v80, v90, v205
	v_exp_f32_e32 v238, v80
	v_sub_f32_e32 v80, v91, v205
	v_exp_f32_e32 v239, v80
	v_sub_f32_e32 v80, v92, v205
	v_exp_f32_e32 v92, v80
	v_add_u32_e32 v80, s12, v182
	v_sub_f32_e32 v81, v96, v204
	v_add_u32_e32 v88, v80, v186
	v_exp_f32_e32 v193, v81
	v_sub_f32_e32 v81, v97, v204
	v_add_u32_e32 v185, 0x4800, v88
	v_add_u32_e32 v187, 0x6800, v88
	v_exp_f32_e32 v206, v81
	ds_read2_b64 v[80:83], v185 offset1:2
	ds_read2_b64 v[88:91], v187 offset0:32 offset1:34
	v_sub_f32_e32 v96, v99, v204
	v_sub_f32_e32 v84, v98, v204
	v_exp_f32_e32 v208, v96
	v_sub_f32_e32 v96, v100, v204
	v_exp_f32_e32 v207, v84
	v_cvt_pk_bf16_f32 v84, v112, v113
	v_cvt_pk_bf16_f32 v85, v114, v115
	v_cvt_pk_bf16_f32 v86, v116, v117
	v_cvt_pk_bf16_f32 v87, v118, v119
	v_exp_f32_e32 v209, v96
	v_sub_f32_e32 v96, v101, v204
	s_waitcnt lgkmcnt(1)
	v_mfma_f32_32x32x16_bf16 v[48:63], v[80:83], v[84:87], v[48:63]
	v_exp_f32_e32 v210, v96
	v_sub_f32_e32 v96, v102, v204
	v_exp_f32_e32 v211, v96
	v_sub_f32_e32 v96, v107, v204
	v_exp_f32_e32 v216, v96
	v_sub_f32_e32 v96, v108, v204
	v_exp_f32_e32 v217, v96
	s_waitcnt lgkmcnt(0)
	v_mfma_f32_32x32x16_bf16 v[32:47], v[88:91], v[84:87], v[32:47]
	v_sub_f32_e32 v84, v103, v204
	v_exp_f32_e32 v212, v84
	v_cvt_pk_bf16_f32 v84, v193, v206
	v_cvt_pk_bf16_f32 v85, v207, v208
	v_cvt_pk_bf16_f32 v86, v209, v210
	v_cvt_pk_bf16_f32 v87, v211, v212
	v_sub_f32_e32 v96, v109, v204
	v_exp_f32_e32 v218, v96
	v_mfma_f32_32x32x16_bf16 v[16:31], v[80:83], v[84:87], v[16:31]
	v_sub_f32_e32 v80, v93, v205
	v_exp_f32_e32 v93, v80
	v_sub_f32_e32 v80, v104, v204
	v_exp_f32_e32 v213, v80
	v_sub_f32_e32 v80, v105, v204
	v_exp_f32_e32 v214, v80
	ds_read2_b64 v[80:83], v185 offset0:4 offset1:6
	v_mfma_f32_32x32x16_bf16 v[0:15], v[88:91], v[84:87], v[0:15]
	ds_read2_b64 v[88:91], v187 offset0:36 offset1:38
	v_sub_f32_e32 v84, v106, v204
	v_exp_f32_e32 v215, v84
	v_cvt_pk_bf16_f32 v84, v120, v121
	v_cvt_pk_bf16_f32 v85, v122, v123
	v_cvt_pk_bf16_f32 v86, v124, v125
	v_cvt_pk_bf16_f32 v87, v126, v127
	v_sub_f32_e32 v96, v110, v204
	v_exp_f32_e32 v219, v96
	s_waitcnt lgkmcnt(1)
	v_mfma_f32_32x32x16_bf16 v[48:63], v[80:83], v[84:87], v[48:63]
	v_sub_f32_e32 v64, v64, v204
	v_exp_f32_e32 v221, v64
	v_sub_f32_e32 v64, v65, v204
	v_exp_f32_e32 v222, v64
	v_sub_f32_e32 v64, v66, v204
	v_exp_f32_e32 v223, v64
	v_sub_f32_e32 v64, v67, v204
	s_waitcnt lgkmcnt(0)
	v_mfma_f32_32x32x16_bf16 v[32:47], v[88:91], v[84:87], v[32:47]
	v_sub_f32_e32 v84, v111, v204
	v_exp_f32_e32 v220, v84
	v_cvt_pk_bf16_f32 v84, v213, v214
	v_cvt_pk_bf16_f32 v85, v215, v216
	v_cvt_pk_bf16_f32 v86, v217, v218
	v_cvt_pk_bf16_f32 v87, v219, v220
	s_nop 1
	v_mfma_f32_32x32x16_bf16 v[16:31], v[80:83], v[84:87], v[16:31]
	v_sub_f32_e32 v80, v94, v205
	v_exp_f32_e32 v94, v80
	ds_read2_b64 v[80:83], v185 offset0:8 offset1:10
	v_mfma_f32_32x32x16_bf16 v[0:15], v[88:91], v[84:87], v[0:15]
	ds_read2_b64 v[88:91], v187 offset0:40 offset1:42
	v_cvt_pk_bf16_f32 v84, v224, v225
	v_exp_f32_e32 v224, v64
	v_sub_f32_e32 v64, v68, v204
	v_exp_f32_e32 v225, v64
	v_sub_f32_e32 v64, v69, v204
	v_cvt_pk_bf16_f32 v85, v184, v226
	v_exp_f32_e32 v226, v64
	v_sub_f32_e32 v64, v70, v204
	v_cvt_pk_bf16_f32 v86, v227, v228
	v_exp_f32_e32 v227, v64
	v_sub_f32_e32 v64, v71, v204
	v_exp_f32_e32 v228, v64
	v_cvt_pk_bf16_f32 v87, v229, v230
	v_sub_f32_e32 v68, v95, v205
	v_cvt_pk_bf16_f32 v64, v221, v222
	s_waitcnt lgkmcnt(1)
; #define LAS __attribute__((address_space(3)))
; __device__ __forceinline__ unsigned pk2(float lo, float hi) { f32x2_t v = {lo, hi}; bf16x2_t b = __builtin_convertvector(v, bf16x2_t); return __builtin_bit_cast(unsigned, b); }
; template <int DK, bool IS_A>
; __device__ __forceinline__ void attn_unit(const Params& P, int l, LAS unsigned char* lds, int b, int grp, int qtok0, int nkeys) {
;     ...
;             __builtin_amdgcn_s_setprio(1);
; #pragma unroll
;             for (int i = 0; i < DK / 16; ++i)
; #pragma unroll
;                 for (int jj = 0; jj < 2; ++jj) {
;                     const bf16x8 kf = *(const LAS bf16x8*)(kb + jj * 32 * AK_PITCH + i * 32);
;                     pa[jj] = __builtin_amdgcn_mfma_f32_32x32x16_bf16(kf, qa[i], pa[jj], 0, 0, 0);
;                     pb[jj] = __builtin_amdgcn_mfma_f32_32x32x16_bf16(kf, qb[i], pb[jj], 0, 0, 0);
;                 }
;             __builtin_amdgcn_s_setprio(0);
;     ...
;             for (int ks = 0; ks < 4; ++ks) {
;                 const int o8 = 8 * (ks & 1);
;                 u32x4 w; const f32x16& xa = pa[ks >> 1]; const f32x16& xb = pb[ks >> 1];
;                 w.x = pk2(xa[o8], xa[o8 + 1]); w.y = pk2(xa[o8 + 2], xa[o8 + 3]); w.z = pk2(xa[o8 + 4], xa[o8 + 5]); w.w = pk2(xa[o8 + 6], xa[o8 + 7]);
;                 const bf16x8 pfa = __builtin_bit_cast(bf16x8, w);
;                 w.x = pk2(xb[o8], xb[o8 + 1]); w.y = pk2(xb[o8 + 2], xb[o8 + 3]); w.z = pk2(xb[o8 + 4], xb[o8 + 5]); w.w = pk2(xb[o8 + 6], xb[o8 + 7]);
;                 const bf16x8 pfb = __builtin_bit_cast(bf16x8, w);
;                 const u32x2 a0 = *(const LAS u32x2*)(vb + ks * 32), a1 = *(const LAS u32x2*)(vb + ks * 32 + 16);
;                 const u32x2 c0 = *(const LAS u32x2*)(vb + 32 * AV_PITCH + ks * 32), c1 = *(const LAS u32x2*)(vb + 32 * AV_PITCH + ks * 32 + 16);
;                 const bf16x8 v0 = __builtin_bit_cast(bf16x8, ((u32x4){a0.x, a0.y, a1.x, a1.y})), v1 = __builtin_bit_cast(bf16x8, ((u32x4){c0.x, c0.y, c1.x, c1.y}));
;                 oa0 = __builtin_amdgcn_mfma_f32_32x32x16_bf16(v0, pfa, oa0, 0, 0, 0);
;                 oa1 = __builtin_amdgcn_mfma_f32_32x32x16_bf16(v1, pfa, oa1, 0, 0, 0);
;                 ob0 = __builtin_amdgcn_mfma_f32_32x32x16_bf16(v0, pfb, ob0, 0, 0, 0);
;                 ob1 = __builtin_amdgcn_mfma_f32_32x32x16_bf16(v1, pfb, ob1, 0, 0, 0);
;             }
	v_mfma_f32_32x32x16_bf16 v[48:63], v[80:83], v[84:87], v[48:63]
	v_cvt_pk_bf16_f32 v65, v223, v224
	v_cvt_pk_bf16_f32 v66, v225, v226
	v_cvt_pk_bf16_f32 v67, v227, v228
	s_waitcnt lgkmcnt(0)
	v_mfma_f32_32x32x16_bf16 v[32:47], v[88:91], v[84:87], v[32:47]
	v_exp_f32_e32 v84, v68
	v_sub_f32_e32 v68, v72, v204
	v_exp_f32_e32 v229, v68
	v_sub_f32_e32 v68, v73, v204
	v_exp_f32_e32 v230, v68
	ds_read2_b64 v[68:71], v185 offset0:12 offset1:14
	v_sub_f32_e32 v72, v75, v204
	v_mfma_f32_32x32x16_bf16 v[16:31], v[80:83], v[64:67], v[16:31]
	ds_read2_b64 v[80:83], v187 offset0:44 offset1:46
	v_exp_f32_e32 v235, v72
	v_sub_f32_e32 v72, v76, v204
	v_exp_f32_e32 v236, v72
	v_sub_f32_e32 v72, v77, v204
	v_mfma_f32_32x32x16_bf16 v[0:15], v[88:91], v[64:67], v[0:15]
	v_sub_f32_e32 v64, v74, v204
	v_exp_f32_e32 v232, v64
	v_cvt_pk_bf16_f32 v64, v231, v233
	v_cvt_pk_bf16_f32 v65, v238, v239
	v_cvt_pk_bf16_f32 v66, v92, v93
	v_cvt_pk_bf16_f32 v67, v94, v84
	v_exp_f32_e32 v231, v72
	v_sub_f32_e32 v72, v78, v204
	s_waitcnt lgkmcnt(1)
	v_mfma_f32_32x32x16_bf16 v[48:63], v[68:71], v[64:67], v[48:63]
	v_exp_f32_e32 v233, v72
	s_waitcnt lgkmcnt(0)
	v_mfma_f32_32x32x16_bf16 v[32:47], v[80:83], v[64:67], v[32:47]
	v_sub_f32_e32 v64, v79, v204
	v_exp_f32_e32 v234, v64
	v_cvt_pk_bf16_f32 v64, v229, v230
	v_cvt_pk_bf16_f32 v65, v232, v235
	v_cvt_pk_bf16_f32 v66, v236, v231
	v_cvt_pk_bf16_f32 v67, v233, v234
	s_nop 1
	v_mfma_f32_32x32x16_bf16 v[16:31], v[68:71], v[64:67], v[16:31]
	v_add_f32_e32 v68, v238, v237
	v_add_f32_e32 v68, v239, v68
	v_add_f32_e32 v68, v92, v68
	v_add_f32_e32 v68, v93, v68
	v_add_f32_e32 v68, v94, v68
	v_add_f32_e32 v68, v84, v68
	v_add_f32_e32 v198, v198, v68
	v_mfma_f32_32x32x16_bf16 v[0:15], v[80:83], v[64:67], v[0:15]
	s_setprio 1
	ds_read_b128 v[64:67], v199 offset:9216
	ds_read_b128 v[238:241], v199 offset:9248
	s_waitcnt lgkmcnt(1)
	v_mfma_f32_32x32x16_bf16 v[112:127], v[64:67], v[142:145], 0
	v_mfma_f32_32x32x16_bf16 v[96:111], v[64:67], v[146:149], 0
	ds_read_b128 v[64:67], v199 offset:13824
	s_waitcnt lgkmcnt(1)
	v_mfma_f32_32x32x16_bf16 v[112:127], v[238:241], v[154:157], v[112:127]
	v_mfma_f32_32x32x16_bf16 v[96:111], v[238:241], v[162:165], v[96:111]
	ds_read_b128 v[238:241], v199 offset:13856
	s_waitcnt lgkmcnt(1)
	v_mfma_f32_32x32x16_bf16 v[80:95], v[64:67], v[142:145], 0
	v_mfma_f32_32x32x16_bf16 v[64:79], v[64:67], v[146:149], 0
	s_waitcnt lgkmcnt(0)
	v_mfma_f32_32x32x16_bf16 v[80:95], v[238:241], v[154:157], v[80:95]
	v_mfma_f32_32x32x16_bf16 v[64:79], v[238:241], v[162:165], v[64:79]
	ds_read_b128 v[238:241], v199 offset:9280
	s_waitcnt lgkmcnt(0)
	v_mfma_f32_32x32x16_bf16 v[112:127], v[238:241], v[158:161], v[112:127]
	v_mfma_f32_32x32x16_bf16 v[96:111], v[238:241], v[170:173], v[96:111]
	ds_read_b128 v[238:241], v199 offset:13888
	s_waitcnt lgkmcnt(0)
	v_mfma_f32_32x32x16_bf16 v[80:95], v[238:241], v[158:161], v[80:95]
	v_mfma_f32_32x32x16_bf16 v[64:79], v[238:241], v[170:173], v[64:79]
	ds_read_b128 v[238:241], v199 offset:9312
	s_waitcnt lgkmcnt(0)
	v_mfma_f32_32x32x16_bf16 v[112:127], v[238:241], v[166:169], v[112:127]
	v_mfma_f32_32x32x16_bf16 v[96:111], v[238:241], v[174:177], v[96:111]
	ds_read_b128 v[238:241], v199 offset:13920
	s_waitcnt lgkmcnt(0)
	v_mfma_f32_32x32x16_bf16 v[80:95], v[238:241], v[166:169], v[80:95]
	v_mfma_f32_32x32x16_bf16 v[64:79], v[238:241], v[174:177], v[64:79]
	s_setprio 0
	s_nop 9
	v_max_f32_e32 v184, v80, v80
	v_max_f32_e32 v199, v112, v112
	v_max_f32_e32 v184, v199, v184
	v_max3_f32 v199, v81, v114, v82
	v_max3_f32 v184, v184, v113, v115
	v_max3_f32 v199, v199, v116, v84
	v_max3_f32 v184, v184, v83, v117
	v_max3_f32 v199, v199, v118, v86
	v_max3_f32 v184, v184, v85, v119
	v_max3_f32 v199, v199, v120, v88
	v_max3_f32 v184, v184, v87, v121
	v_max3_f32 v199, v199, v122, v90
	v_max3_f32 v184, v184, v89, v123
	v_max3_f32 v199, v199, v124, v92
	v_max3_f32 v184, v184, v91, v125
	v_max3_f32 v199, v199, v126, v94
	v_max3_f32 v184, v184, v93, v127
	v_max3_f32 v184, v184, v95, v199
	v_mov_b32_e32 v199, v184
	s_waitcnt lgkmcnt(0)
	s_nop 1
	v_permlane32_swap_b32_e32 v184, v199
	v_max3_f32 v184, v205, v184, v199
	v_cmp_gt_f32_e32 vcc, v184, v205
	s_cbranch_vccz .LBB0_453
	v_sub_f32_e32 v199, v205, v184
	v_exp_f32_e32 v238, v199
	s_nop 0
	v_pk_mul_f32 v[62:63], v[62:63], v[238:239] op_sel_hi:[1,0]
	v_pk_mul_f32 v[60:61], v[60:61], v[238:239] op_sel_hi:[1,0]
	v_pk_mul_f32 v[58:59], v[58:59], v[238:239] op_sel_hi:[1,0]
	v_pk_mul_f32 v[56:57], v[56:57], v[238:239] op_sel_hi:[1,0]
	v_pk_mul_f32 v[54:55], v[54:55], v[238:239] op_sel_hi:[1,0]
	v_pk_mul_f32 v[52:53], v[52:53], v[238:239] op_sel_hi:[1,0]
	v_pk_mul_f32 v[50:51], v[50:51], v[238:239] op_sel_hi:[1,0]
	v_pk_mul_f32 v[48:49], v[48:49], v[238:239] op_sel_hi:[1,0]
	v_pk_mul_f32 v[46:47], v[46:47], v[238:239] op_sel_hi:[1,0]
	v_pk_mul_f32 v[44:45], v[44:45], v[238:239] op_sel_hi:[1,0]
	v_pk_mul_f32 v[42:43], v[42:43], v[238:239] op_sel_hi:[1,0]
	v_pk_mul_f32 v[40:41], v[40:41], v[238:239] op_sel_hi:[1,0]
	v_pk_mul_f32 v[38:39], v[38:39], v[238:239] op_sel_hi:[1,0]
	v_pk_mul_f32 v[36:37], v[36:37], v[238:239] op_sel_hi:[1,0]
	v_pk_mul_f32 v[34:35], v[34:35], v[238:239] op_sel_hi:[1,0]
	v_pk_mul_f32 v[32:33], v[32:33], v[238:239] op_sel_hi:[1,0]
	v_mul_f32_e32 v198, v198, v238
	s_branch .LBB0_454

.LBB0_454:
	v_add_f32_e32 v193, 0, v193
	v_add_f32_e32 v193, v206, v193
	v_add_f32_e32 v193, v207, v193
	v_add_f32_e32 v193, v208, v193
	v_add_f32_e32 v193, v209, v193
	v_add_f32_e32 v193, v210, v193
	v_add_f32_e32 v193, v211, v193
	v_add_f32_e32 v193, v212, v193
	v_add_f32_e32 v193, v213, v193
	v_add_f32_e32 v193, v214, v193
	v_add_f32_e32 v193, v215, v193
	v_add_f32_e32 v193, v216, v193
	v_add_f32_e32 v193, v217, v193
	v_add_f32_e32 v193, v218, v193
	v_add_f32_e32 v193, v219, v193
	v_add_f32_e32 v193, v220, v193
	v_add_f32_e32 v193, v221, v193
	v_add_f32_e32 v193, v222, v193
	v_max_f32_e32 v199, v64, v64
	v_max_f32_e32 v205, v96, v96
	v_add_f32_e32 v193, v223, v193
	v_max_f32_e32 v199, v205, v199
	v_add_f32_e32 v193, v224, v193
	v_max3_f32 v205, v65, v98, v66
	v_max3_f32 v199, v199, v97, v99
	v_add_f32_e32 v193, v225, v193
	v_max3_f32 v205, v205, v100, v68
	v_max3_f32 v199, v199, v67, v101
	v_add_f32_e32 v193, v226, v193
	v_max3_f32 v205, v205, v102, v70
	v_max3_f32 v199, v199, v69, v103
	v_add_f32_e32 v193, v227, v193
	v_max3_f32 v205, v205, v104, v72
	v_max3_f32 v199, v199, v71, v105
	v_add_f32_e32 v193, v228, v193
	v_max3_f32 v205, v205, v106, v74
	v_max3_f32 v199, v199, v73, v107
	v_add_f32_e32 v193, v229, v193
	v_max3_f32 v205, v205, v108, v76
	v_max3_f32 v199, v199, v75, v109
	v_add_f32_e32 v193, v230, v193
	v_max3_f32 v205, v205, v110, v78
	v_max3_f32 v199, v199, v77, v111
	v_add_f32_e32 v193, v232, v193
	v_max3_f32 v199, v199, v79, v205
	v_add_f32_e32 v193, v235, v193
	v_mov_b32_e32 v205, v199
	v_add_f32_e32 v193, v236, v193
	v_add_f32_e32 v193, v231, v193
	v_add_f32_e32 v193, v233, v193
	v_add_f32_e32 v193, v234, v193
	v_add_f32_e32 v183, v183, v193
	s_waitcnt lgkmcnt(0)
	v_permlane32_swap_b32_e32 v199, v205
	v_max3_f32 v193, v204, v199, v205
	v_cmp_gt_f32_e32 vcc, v193, v204
	s_cbranch_vccz .LBB0_456
	v_sub_f32_e32 v199, v204, v193
	v_exp_f32_e32 v204, v199
	s_nop 0
	v_pk_mul_f32 v[30:31], v[30:31], v[204:205] op_sel_hi:[1,0]
	v_pk_mul_f32 v[28:29], v[28:29], v[204:205] op_sel_hi:[1,0]
	v_pk_mul_f32 v[26:27], v[26:27], v[204:205] op_sel_hi:[1,0]
	v_pk_mul_f32 v[24:25], v[24:25], v[204:205] op_sel_hi:[1,0]
	v_pk_mul_f32 v[22:23], v[22:23], v[204:205] op_sel_hi:[1,0]
	v_pk_mul_f32 v[20:21], v[20:21], v[204:205] op_sel_hi:[1,0]
	v_pk_mul_f32 v[18:19], v[18:19], v[204:205] op_sel_hi:[1,0]
	v_pk_mul_f32 v[16:17], v[16:17], v[204:205] op_sel_hi:[1,0]
	v_pk_mul_f32 v[14:15], v[14:15], v[204:205] op_sel_hi:[1,0]
	v_pk_mul_f32 v[12:13], v[12:13], v[204:205] op_sel_hi:[1,0]
	v_pk_mul_f32 v[10:11], v[10:11], v[204:205] op_sel_hi:[1,0]
	v_pk_mul_f32 v[8:9], v[8:9], v[204:205] op_sel_hi:[1,0]
	v_pk_mul_f32 v[6:7], v[6:7], v[204:205] op_sel_hi:[1,0]
	v_pk_mul_f32 v[4:5], v[4:5], v[204:205] op_sel_hi:[1,0]
	v_pk_mul_f32 v[2:3], v[2:3], v[204:205] op_sel_hi:[1,0]
	v_pk_mul_f32 v[0:1], v[0:1], v[204:205] op_sel_hi:[1,0]
	v_mul_f32_e32 v183, v183, v204
	s_branch .LBB0_457
